# attention QK: every segment ordered so same-accumulator MFMAs are adjacent (incl. final D!=C segment), all three unmasked loops
# speedup vs baseline: 1.0032x; 1.0008x over previous
.LBB0_626:
	s_lshl_b32 s2, s9, 14
	s_add_i32 s2, s58, s2
	v_lshl_add_u64 v[2:3], s[60:61], 0, v[0:1]
	v_lshl_add_u64 v[2:3], v[2:3], 0, s[96:97]
	s_mov_b32 m0, s2
	v_mov_b32_e32 v15, v1
	global_load_lds_dwordx4 v[2:3], off
	v_lshl_add_u64 v[2:3], s[60:61], 0, v[14:15]
	v_lshl_add_u64 v[2:3], v[2:3], 0, s[96:97]
	s_add_i32 m0, s2, 0x2000
	s_cmp_lt_u32 s27, s59
	global_load_lds_dwordx4 v[2:3], off
	s_cselect_b64 vcc, -1, 0
	v_add_u32_e32 v2, 0x30000, v0
	v_add_u32_e32 v3, 0x30000, v14
	s_cmp_lg_u64 vcc, 0
	v_cndmask_b32_e32 v14, v14, v3, vcc
	v_cndmask_b32_e32 v0, v0, v2, vcc
	s_addc_u32 s27, s27, 0
	s_mul_i32 s2, s12, 0x6000
	v_add_u32_e32 v15, s2, v236
	v_add_u32_e32 v6, v15, v241
	ds_read_b128 v[2:5], v6
	ds_read_b128 v[6:9], v6 offset:12288
	v_exp_f32_e32 v12, v96
	s_waitcnt lgkmcnt(0)
	v_mfma_f32_32x32x16_bf16 v[112:127], v[2:5], v[144:147], 0
	v_mov_b32_e32 v2, v97
	v_exp_f32_e32 v96, v98
	v_exp_f32_e32 v97, v99
	v_exp_f32_e32 v13, v2
	v_mfma_f32_32x32x16_bf16 v[128:143], v[6:9], v[144:147], 0
	v_add_u32_e32 v2, v15, v242
	ds_read_b128 v[4:7], v2
	ds_read_b128 v[8:11], v2 offset:12288
	v_mov_b32_e32 v2, v100
	v_mov_b32_e32 v3, v101
	v_exp_f32_e32 v98, v2
	v_exp_f32_e32 v99, v3
	v_exp_f32_e32 v100, v102
	v_exp_f32_e32 v101, v103
	v_cvt_pk_bf16_f32 v2, v12, v13
	s_waitcnt lgkmcnt(0)
	v_mfma_f32_32x32x16_bf16 v[128:143], v[8:11], v[148:151], v[128:143]
	v_mfma_f32_32x32x16_bf16 v[112:127], v[4:7], v[148:151], v[112:127]
	v_cvt_pk_bf16_f32 v3, v96, v97
	v_cvt_pk_bf16_f32 v4, v98, v99
	v_cvt_pk_bf16_f32 v5, v100, v101
	s_nop 0
	v_permlane32_swap_b32_e32 v2, v4
	v_permlane32_swap_b32_e32 v3, v5
	v_add_u32_e32 v10, v15, v243
	ds_read_b128 v[6:9], v10
	v_add_f32_e64 v102, v214, v12
	v_add_f32_e64 v103, v215, v13
	ds_read_b128 v[10:13], v10 offset:12288
	v_exp_f32_e32 v104, v104
	v_exp_f32_e32 v105, v105
	s_waitcnt lgkmcnt(0)
	v_mfma_f32_32x32x16_bf16 v[112:127], v[6:9], v[152:155], v[112:127]
	v_add_f32_e64 v6, v96, v102
	v_add_f32_e64 v7, v97, v103
	v_exp_f32_e32 v102, v106
	v_exp_f32_e32 v103, v107
	v_pk_add_f32 v[6:7], v[98:99], v[6:7]
	s_nop 0
	v_pk_add_f32 v[6:7], v[100:101], v[6:7]
	s_nop 0
	v_pk_add_f32 v[100:101], v[104:105], v[6:7]
	v_mfma_f32_32x32x16_bf16 v[128:143], v[10:13], v[152:155], v[128:143]
	v_add_u32_e32 v6, v15, v244
	ds_read_b128 v[8:11], v6
	ds_read_b128 v[96:99], v6 offset:12288
	v_exp_f32_e32 v106, v108
	v_exp_f32_e32 v107, v109
	v_exp_f32_e32 v108, v110
	v_exp_f32_e32 v109, v111
	v_cvt_pk_bf16_f32 v6, v104, v105
	s_waitcnt lgkmcnt(0)
	v_mfma_f32_32x32x16_bf16 v[128:143], v[96:99], v[156:159], v[128:143]
	v_mfma_f32_32x32x16_bf16 v[112:127], v[8:11], v[156:159], v[112:127]
	v_cvt_pk_bf16_f32 v7, v102, v103
	v_cvt_pk_bf16_f32 v8, v106, v107
	v_cvt_pk_bf16_f32 v9, v108, v109
	s_nop 0
	v_permlane32_swap_b32_e32 v6, v8
	v_permlane32_swap_b32_e32 v7, v9
	v_add_u32_e32 v96, v15, v245
	ds_read_b128 v[10:13], v96
	ds_read_b128 v[96:99], v96 offset:12288
	v_exp_f32_e32 v104, v80
	s_waitcnt lgkmcnt(0)
	v_mfma_f32_32x32x16_bf16 v[112:127], v[10:13], v[160:163], v[112:127]
	v_exp_f32_e32 v105, v81
	v_exp_f32_e32 v110, v82
	v_exp_f32_e32 v111, v83
	v_mfma_f32_32x32x16_bf16 v[128:143], v[96:99], v[160:163], v[128:143]
	v_add_u32_e32 v80, v15, v246
	ds_read_b128 v[10:13], v80
	ds_read_b128 v[80:83], v80 offset:12288
	v_exp_f32_e32 v96, v84
	v_exp_f32_e32 v97, v85
	v_exp_f32_e32 v98, v86
	v_exp_f32_e32 v99, v87
	v_cvt_pk_bf16_f32 v192, v104, v105
	v_cvt_pk_bf16_f32 v193, v110, v111
	v_cvt_pk_bf16_f32 v194, v96, v97
	v_cvt_pk_bf16_f32 v195, v98, v99
	s_waitcnt lgkmcnt(0)
	v_mfma_f32_32x32x16_bf16 v[128:143], v[80:83], v[164:167], v[128:143]
	v_permlane32_swap_b32_e32 v192, v194
	v_permlane32_swap_b32_e32 v193, v195
	v_mfma_f32_32x32x16_bf16 v[112:127], v[10:13], v[164:167], v[112:127]
	v_add_u32_e32 v80, v15, v247
	ds_read_b128 v[10:13], v80
	ds_read_b128 v[80:83], v80 offset:12288
	s_waitcnt lgkmcnt(0)
	v_mfma_f32_32x32x16_bf16 v[112:127], v[10:13], v[168:171], v[112:127]
	v_exp_f32_e32 v10, v88
	v_exp_f32_e32 v11, v89
	v_exp_f32_e32 v12, v90
	v_exp_f32_e32 v13, v91
	v_mfma_f32_32x32x16_bf16 v[128:143], v[80:83], v[168:171], v[128:143]
	v_mov_b32_e32 v88, v92
	v_mov_b32_e32 v89, v93
	v_add_f32_e64 v92, v102, v100
	v_add_f32_e64 v93, v103, v101
	v_add_u32_e32 v84, v15, v248
	v_pk_add_f32 v[92:93], v[106:107], v[92:93]
	v_pk_add_f32 v[92:93], v[108:109], v[92:93]
	v_pk_add_f32 v[92:93], v[104:105], v[92:93]
	v_exp_f32_e32 v88, v88
	v_pk_add_f32 v[92:93], v[110:111], v[92:93]
	v_exp_f32_e32 v89, v89
	v_pk_add_f32 v[92:93], v[96:97], v[92:93]
	ds_read_b128 v[80:83], v84
	ds_read_b128 v[84:87], v84 offset:12288
	v_exp_f32_e32 v90, v94
	v_exp_f32_e32 v91, v95
	v_pk_add_f32 v[92:93], v[98:99], v[92:93]
	s_waitcnt lgkmcnt(0)
; #define SBAR() __builtin_amdgcn_sched_barrier(0)
; #define VSET(S, d0) do { constexpr int b_ = (d0) * 512; TRRD(S##l0, b_); TRRD(S##h0, b_ + 2048); TRRD(S##l1, b_ + 4096); TRRD(S##h1, b_ + 6144); \
;         TRRD(S##l2, b_ + 8192); TRRD(S##h2, b_ + 10240); TRRD(S##l3, b_ + 12288); TRRD(S##h3, b_ + 14336); } while (0)
; #define LWAIT(n) do { asm volatile("s_waitcnt lgkmcnt(" #n ")" ::: "memory"); SBAR(); } while (0)
; __device__ __forceinline__ void pv_tile(f32x16* o, unsigned vb, bf16x8 pa0, bf16x8 pa1, bf16x8 pa2, bf16x8 pa3) {
;     ...
;     s16x4 Al0, Al1, Al2, Al3, Ah0, Ah1, Ah2, Ah3, Bl0, Bl1, Bl2, Bl3, Bh0, Bh1, Bh2, Bh3;
;     VSET(A, 0);
;     VSET(B, 1); LWAIT(8); VMMA(A, 0); SBAR();
;     VSET(A, 2); LWAIT(8); VMMA(B, 1); SBAR();
;     VSET(B, 3); LWAIT(8); VMMA(A, 2); SBAR();
;     LWAIT(0); VMMA(B, 3);
	v_mfma_f32_32x32x16_bf16 v[128:143], v[84:87], v[172:175], v[128:143]
	v_add_f32_e64 v92, v10, v92
	v_add_f32_e64 v93, v11, v93
	v_cvt_pk_bf16_f32 v10, v10, v11
	v_add_f32_e64 v92, v12, v92
	v_add_f32_e64 v93, v13, v93
	v_cvt_pk_bf16_f32 v11, v12, v13
	v_pk_add_f32 v[92:93], v[88:89], v[92:93]
	v_cvt_pk_bf16_f32 v12, v88, v89
	v_pk_add_f32 v[214:215], v[90:91], v[92:93]
	v_cvt_pk_bf16_f32 v13, v90, v91
	v_permlane32_swap_b32_e32 v10, v12
	s_nop 0
	v_permlane32_swap_b32_e32 v11, v13
	v_mfma_f32_32x32x16_bf16 v[112:127], v[80:83], v[172:175], v[112:127]
	v_add_u32_e32 v92, v15, v249
	v_add_u32_e32 v93, v15, v250
	v_add_u32_e32 v94, v15, v251
	v_add_u32_e32 v95, v15, v252
	ds_read_b128 v[96:99], v92
	ds_read_b128 v[100:103], v93
	ds_read_b128 v[104:107], v94
	ds_read_b128 v[80:83], v92 offset:12288
	ds_read_b128 v[84:87], v93 offset:12288
	ds_read_b128 v[88:91], v94 offset:12288
	ds_read_b128 v[222:225], v95 offset:12288
	ds_read_b128 v[92:95], v95
	s_waitcnt lgkmcnt(7)
	v_mfma_f32_32x32x16_bf16 v[112:127], v[96:99], v[176:179], v[112:127]
	s_waitcnt lgkmcnt(6)
	v_mfma_f32_32x32x16_bf16 v[112:127], v[100:103], v[180:183], v[112:127]
	s_waitcnt lgkmcnt(5)
	v_mfma_f32_32x32x16_bf16 v[112:127], v[104:107], v[184:187], v[112:127]
	s_waitcnt lgkmcnt(0)
	v_mfma_f32_32x32x16_bf16 v[96:111], v[92:95], v[188:191], v[112:127]
	v_mfma_f32_32x32x16_bf16 v[128:143], v[80:83], v[176:179], v[128:143]
	v_mfma_f32_32x32x16_bf16 v[128:143], v[84:87], v[180:183], v[128:143]
	v_mfma_f32_32x32x16_bf16 v[128:143], v[88:91], v[184:187], v[128:143]
	v_mfma_f32_32x32x16_bf16 v[80:95], v[222:225], v[188:191], v[128:143]
	v_lshl_add_u32 v15, s7, 14, v237
	ds_read_b64_tr_b16 v[112:113], v15 offset:0
	ds_read_b64_tr_b16 v[114:115], v15 offset:0x800
	ds_read_b64_tr_b16 v[116:117], v15 offset:0x1000
	ds_read_b64_tr_b16 v[118:119], v15 offset:0x1800
	ds_read_b64_tr_b16 v[120:121], v15 offset:0x2000
	ds_read_b64_tr_b16 v[122:123], v15 offset:0x2800
	ds_read_b64_tr_b16 v[124:125], v15 offset:0x3000
	ds_read_b64_tr_b16 v[126:127], v15 offset:0x3800
	ds_read_b64_tr_b16 v[128:129], v15 offset:0x200
	ds_read_b64_tr_b16 v[130:131], v15 offset:0xa00
	ds_read_b64_tr_b16 v[132:133], v15 offset:0x1200
	ds_read_b64_tr_b16 v[134:135], v15 offset:0x1a00
	ds_read_b64_tr_b16 v[136:137], v15 offset:0x2200
	ds_read_b64_tr_b16 v[138:139], v15 offset:0x2a00
	ds_read_b64_tr_b16 v[140:141], v15 offset:0x3200
	ds_read_b64_tr_b16 v[142:143], v15 offset:0x3a00
	s_waitcnt lgkmcnt(8)
	s_nop 0
	v_mfma_f32_32x32x16_bf16 v[64:79], v[2:5], v[112:115], v[64:79]
	v_mfma_f32_32x32x16_bf16 v[64:79], v[6:9], v[116:119], v[64:79]
	v_mfma_f32_32x32x16_bf16 v[64:79], v[192:195], v[120:123], v[64:79]
	v_mfma_f32_32x32x16_bf16 v[64:79], v[10:13], v[124:127], v[64:79]
	ds_read_b64_tr_b16 v[112:113], v15 offset:0x400
	ds_read_b64_tr_b16 v[114:115], v15 offset:0xc00
	ds_read_b64_tr_b16 v[116:117], v15 offset:0x1400
	ds_read_b64_tr_b16 v[118:119], v15 offset:0x1c00
	ds_read_b64_tr_b16 v[120:121], v15 offset:0x2400
	ds_read_b64_tr_b16 v[122:123], v15 offset:0x2c00
	ds_read_b64_tr_b16 v[124:125], v15 offset:0x3400
	ds_read_b64_tr_b16 v[126:127], v15 offset:0x3c00
	s_waitcnt lgkmcnt(8)
	v_mfma_f32_32x32x16_bf16 v[48:63], v[2:5], v[128:131], v[48:63]
	v_mfma_f32_32x32x16_bf16 v[48:63], v[6:9], v[132:135], v[48:63]
	v_mfma_f32_32x32x16_bf16 v[48:63], v[192:195], v[136:139], v[48:63]
	v_mfma_f32_32x32x16_bf16 v[48:63], v[10:13], v[140:143], v[48:63]
	ds_read_b64_tr_b16 v[128:129], v15 offset:0x600
	ds_read_b64_tr_b16 v[130:131], v15 offset:0xe00
	ds_read_b64_tr_b16 v[132:133], v15 offset:0x1600
	ds_read_b64_tr_b16 v[134:135], v15 offset:0x1e00
	ds_read_b64_tr_b16 v[136:137], v15 offset:0x2600
	ds_read_b64_tr_b16 v[138:139], v15 offset:0x2e00
	ds_read_b64_tr_b16 v[140:141], v15 offset:0x3600
	ds_read_b64_tr_b16 v[142:143], v15 offset:0x3e00
	s_waitcnt lgkmcnt(8)
	v_mfma_f32_32x32x16_bf16 v[32:47], v[2:5], v[112:115], v[32:47]
	v_mfma_f32_32x32x16_bf16 v[32:47], v[6:9], v[116:119], v[32:47]
	v_mfma_f32_32x32x16_bf16 v[32:47], v[192:195], v[120:123], v[32:47]
	v_mfma_f32_32x32x16_bf16 v[32:47], v[10:13], v[124:127], v[32:47]
	s_waitcnt lgkmcnt(0)
	v_mfma_f32_32x32x16_bf16 v[16:31], v[2:5], v[128:131], v[16:31]
	s_waitcnt vmcnt(5)
	s_barrier
	s_add_i32 s13, s13, -1
	s_cmp_eq_u32 s13, 0
	v_mfma_f32_32x32x16_bf16 v[16:31], v[6:9], v[132:135], v[16:31]
	v_mfma_f32_32x32x16_bf16 v[16:31], v[192:195], v[136:139], v[16:31]
	v_mfma_f32_32x32x16_bf16 v[16:31], v[10:13], v[140:143], v[16:31]
	s_cbranch_scc1 .LBB0_629
	s_mov_b32 s2, s12
	s_mov_b32 s12, s9
	s_mov_b32 s9, s7
	s_branch .LBB0_624

.LBB0_821:
	s_mov_b32 s12, s14
	s_lshl_b32 s14, s2, 14
	s_mov_b32 s63, s70
	s_mov_b32 s70, s2
	s_add_i32 s2, s9, s14
	s_add_i32 m0, s2, 0xc000
	v_add_u32_e32 v0, 0x98000, v163
	global_load_lds_dwordx4 v165, s[60:61]
	s_add_i32 m0, s2, 0xe000
	s_cmp_lt_u32 s83, s57
	s_cselect_b64 s[18:19], -1, 0
	s_and_b64 s[34:35], s[18:19], exec
	s_cselect_b32 s2, 0x98000, 0
	s_cmp_lg_u64 s[18:19], 0
	global_load_lds_dwordx4 v164, s[60:61]
	v_add_u32_e32 v164, s2, v164
	v_add_u32_e32 v165, s2, v165
	s_addc_u32 s83, s83, 0
	s_lshl_b32 s2, s63, 14
	s_add_i32 s2, s9, s2
	s_mov_b32 m0, s2
	v_add_u32_e32 v98, 0x98000, v162
	global_load_lds_dwordx4 v163, s[76:77]
	s_add_i32 m0, s2, 0x2000
	s_cmp_lt_u32 s62, s57
	global_load_lds_dwordx4 v162, s[76:77]
	s_cselect_b64 vcc, -1, 0
	s_cmp_lg_u64 vcc, 0
	v_cndmask_b32_e32 v162, v162, v98, vcc
	v_cndmask_b32_e32 v163, v163, v0, vcc
	s_addc_u32 s62, s62, 0
	v_lshl_add_u32 v0, s12, 14, v160
	v_add_u32_e32 v102, v0, v166
	v_exp_f32_e32 v150, v82
	v_exp_f32_e32 v151, v83
	v_exp_f32_e32 v152, v84
	v_exp_f32_e32 v153, v85
	ds_read_b128 v[98:101], v102
	ds_read_b128 v[114:117], v102 offset:8192
	v_exp_f32_e32 v170, v86
	v_exp_f32_e32 v171, v87
	v_exp_f32_e32 v172, v88
	v_exp_f32_e32 v173, v89
	v_cvt_pk_bf16_f32 v146, v150, v151
	v_cvt_pk_bf16_f32 v147, v152, v153
	v_cvt_pk_bf16_f32 v148, v170, v171
	v_cvt_pk_bf16_f32 v149, v172, v173
	s_waitcnt lgkmcnt(0)
	v_mfma_f32_32x32x16_bf16 v[114:129], v[114:117], v[130:133], 0
	v_permlane32_swap_b32_e32 v146, v148
	v_permlane32_swap_b32_e32 v147, v149
	v_mfma_f32_32x32x16_bf16 v[98:113], v[98:101], v[130:133], 0
	v_add_u32_e32 v86, v0, v167
	v_mov_b32_e32 v174, v92
	v_mov_b32_e32 v175, v93
	ds_read_b128 v[82:85], v86
	ds_read_b128 v[86:89], v86 offset:8192
	v_exp_f32_e32 v90, v90
	v_exp_f32_e32 v91, v91
	v_pk_add_f32 v[92:93], v[156:157], v[150:151]
	v_exp_f32_e32 v156, v174
	v_exp_f32_e32 v157, v175
	v_exp_f32_e32 v174, v94
	v_exp_f32_e32 v175, v95
	v_exp_f32_e32 v176, v96
	v_exp_f32_e32 v177, v97
	v_pk_add_f32 v[92:93], v[152:153], v[92:93]
	v_cvt_pk_bf16_f32 v150, v90, v91
	v_pk_add_f32 v[92:93], v[170:171], v[92:93]
	v_cvt_pk_bf16_f32 v151, v156, v157
	v_pk_add_f32 v[92:93], v[172:173], v[92:93]
	v_cvt_pk_bf16_f32 v152, v174, v175
	v_pk_add_f32 v[92:93], v[90:91], v[92:93]
	v_cvt_pk_bf16_f32 v153, v176, v177
	s_waitcnt lgkmcnt(0)
	v_mfma_f32_32x32x16_bf16 v[98:113], v[82:85], v[134:137], v[98:113]
	v_permlane32_swap_b32_e32 v150, v152
	v_permlane32_swap_b32_e32 v151, v153
	v_mfma_f32_32x32x16_bf16 v[114:129], v[86:89], v[134:137], v[114:129]
	v_add_u32_e32 v86, v0, v168
	v_exp_f32_e32 v178, v66
	v_exp_f32_e32 v179, v67
	v_exp_f32_e32 v180, v68
	v_exp_f32_e32 v181, v69
	ds_read_b128 v[82:85], v86
	ds_read_b128 v[86:89], v86 offset:8192
	v_exp_f32_e32 v182, v70
	v_exp_f32_e32 v183, v71
	v_exp_f32_e32 v184, v72
	v_exp_f32_e32 v185, v73
	v_cvt_pk_bf16_f32 v170, v178, v179
	v_cvt_pk_bf16_f32 v171, v180, v181
	v_cvt_pk_bf16_f32 v172, v182, v183
	v_cvt_pk_bf16_f32 v173, v184, v185
	s_waitcnt lgkmcnt(0)
	v_mfma_f32_32x32x16_bf16 v[114:129], v[86:89], v[138:141], v[114:129]
	v_permlane32_swap_b32_e32 v170, v172
	v_permlane32_swap_b32_e32 v171, v173
	v_mfma_f32_32x32x16_bf16 v[98:113], v[82:85], v[138:141], v[98:113]
	v_add_u32_e32 v0, v0, v169
	v_add_f32_e64 v156, v156, v92
	v_add_f32_e64 v157, v157, v93
	ds_read_b128 v[232:235], v0
	ds_read_b128 v[236:239], v0 offset:8192
	v_mov_b32_e32 v193, v81
	v_pk_add_f32 v[248:249], v[174:175], v[156:157]
	v_exp_f32_e32 v240, v74
	v_pk_add_f32 v[248:249], v[176:177], v[248:249]
	v_exp_f32_e32 v241, v75
	v_pk_add_f32 v[248:249], v[178:179], v[248:249]
	s_waitcnt lgkmcnt(0)
; #define SBAR() __builtin_amdgcn_sched_barrier(0)
; #define VSET(S, d0) do { constexpr int b_ = (d0) * 512; TRRD(S##l0, b_); TRRD(S##h0, b_ + 2048); TRRD(S##l1, b_ + 4096); TRRD(S##h1, b_ + 6144); \
;         TRRD(S##l2, b_ + 8192); TRRD(S##h2, b_ + 10240); TRRD(S##l3, b_ + 12288); TRRD(S##h3, b_ + 14336); } while (0)
; #define LWAIT(n) do { asm volatile("s_waitcnt lgkmcnt(" #n ")" ::: "memory"); SBAR(); } while (0)
; __device__ __forceinline__ void pv_tile(f32x16* o, unsigned vb, bf16x8 pa0, bf16x8 pa1, bf16x8 pa2, bf16x8 pa3) {
;     ...
;     s16x4 Al0, Al1, Al2, Al3, Ah0, Ah1, Ah2, Ah3, Bl0, Bl1, Bl2, Bl3, Bh0, Bh1, Bh2, Bh3;
;     VSET(A, 0);
;     VSET(B, 1); LWAIT(8); VMMA(A, 0); SBAR();
;     VSET(A, 2); LWAIT(8); VMMA(B, 1); SBAR();
;     VSET(B, 3); LWAIT(8); VMMA(A, 2); SBAR();
;     LWAIT(0); VMMA(B, 3);
	v_mfma_f32_32x32x16_bf16 v[82:97], v[232:235], v[142:145], v[98:113]
	v_exp_f32_e32 v242, v76
	v_exp_f32_e32 v243, v77
	v_pk_add_f32 v[250:251], v[180:181], v[248:249]
	v_exp_f32_e32 v244, v78
	v_exp_f32_e32 v245, v79
	v_pk_add_f32 v[248:249], v[182:183], v[250:251]
	v_exp_f32_e32 v246, v80
	v_mfma_f32_32x32x16_bf16 v[66:81], v[236:239], v[142:145], v[114:129]
	v_exp_f32_e32 v247, v193
	v_pk_add_f32 v[248:249], v[184:185], v[248:249]
	v_cvt_pk_bf16_f32 v98, v240, v241
	v_pk_add_f32 v[250:251], v[240:241], v[248:249]
	v_cvt_pk_bf16_f32 v99, v242, v243
	v_pk_add_f32 v[250:251], v[242:243], v[250:251]
	v_cvt_pk_bf16_f32 v100, v244, v245
	v_pk_add_f32 v[250:251], v[244:245], v[250:251]
	v_cvt_pk_bf16_f32 v101, v246, v247
	v_pk_add_f32 v[156:157], v[246:247], v[250:251]
	v_permlane32_swap_b32_e32 v98, v100
	v_permlane32_swap_b32_e32 v99, v101
	v_add_u32_e32 v0, s14, v161
	ds_read_b64_tr_b16 v[102:103], v0 offset:0
	ds_read_b64_tr_b16 v[104:105], v0 offset:0x800
	ds_read_b64_tr_b16 v[106:107], v0 offset:0x1000
	ds_read_b64_tr_b16 v[108:109], v0 offset:0x1800
	ds_read_b64_tr_b16 v[110:111], v0 offset:0x2000
	ds_read_b64_tr_b16 v[112:113], v0 offset:0x2800
	ds_read_b64_tr_b16 v[114:115], v0 offset:0x3000
	ds_read_b64_tr_b16 v[116:117], v0 offset:0x3800
	ds_read_b64_tr_b16 v[118:119], v0 offset:0x200
	ds_read_b64_tr_b16 v[120:121], v0 offset:0xa00
	ds_read_b64_tr_b16 v[122:123], v0 offset:0x1200
	ds_read_b64_tr_b16 v[124:125], v0 offset:0x1a00
	ds_read_b64_tr_b16 v[126:127], v0 offset:0x2200
	ds_read_b64_tr_b16 v[128:129], v0 offset:0x2a00
	ds_read_b64_tr_b16 v[174:175], v0 offset:0x3200
	ds_read_b64_tr_b16 v[176:177], v0 offset:0x3a00
	s_waitcnt lgkmcnt(8)
	s_nop 0
	v_mfma_f32_32x32x16_bf16 v[50:65], v[146:149], v[102:105], v[50:65]
	v_mfma_f32_32x32x16_bf16 v[50:65], v[150:153], v[106:109], v[50:65]
	v_mfma_f32_32x32x16_bf16 v[50:65], v[170:173], v[110:113], v[50:65]
	v_mfma_f32_32x32x16_bf16 v[50:65], v[98:101], v[114:117], v[50:65]
	ds_read_b64_tr_b16 v[102:103], v0 offset:0x400
	ds_read_b64_tr_b16 v[104:105], v0 offset:0xc00
	ds_read_b64_tr_b16 v[106:107], v0 offset:0x1400
	ds_read_b64_tr_b16 v[108:109], v0 offset:0x1c00
	ds_read_b64_tr_b16 v[110:111], v0 offset:0x2400
	ds_read_b64_tr_b16 v[112:113], v0 offset:0x2c00
	ds_read_b64_tr_b16 v[114:115], v0 offset:0x3400
	ds_read_b64_tr_b16 v[116:117], v0 offset:0x3c00
	s_waitcnt lgkmcnt(8)
	v_mfma_f32_32x32x16_bf16 v[34:49], v[146:149], v[118:121], v[34:49]
	v_mfma_f32_32x32x16_bf16 v[34:49], v[150:153], v[122:125], v[34:49]
	v_mfma_f32_32x32x16_bf16 v[34:49], v[170:173], v[126:129], v[34:49]
	v_mfma_f32_32x32x16_bf16 v[34:49], v[98:101], v[174:177], v[34:49]
	ds_read_b64_tr_b16 v[118:119], v0 offset:0x600
	ds_read_b64_tr_b16 v[120:121], v0 offset:0xe00
	ds_read_b64_tr_b16 v[122:123], v0 offset:0x1600
	ds_read_b64_tr_b16 v[124:125], v0 offset:0x1e00
	ds_read_b64_tr_b16 v[126:127], v0 offset:0x2600
	ds_read_b64_tr_b16 v[128:129], v0 offset:0x2e00
	ds_read_b64_tr_b16 v[174:175], v0 offset:0x3600
	ds_read_b64_tr_b16 v[176:177], v0 offset:0x3e00
	s_waitcnt lgkmcnt(8)
	v_mfma_f32_32x32x16_bf16 v[18:33], v[146:149], v[102:105], v[18:33]
	v_mfma_f32_32x32x16_bf16 v[18:33], v[150:153], v[106:109], v[18:33]
	v_mfma_f32_32x32x16_bf16 v[18:33], v[170:173], v[110:113], v[18:33]
	v_mfma_f32_32x32x16_bf16 v[18:33], v[98:101], v[114:117], v[18:33]
	s_waitcnt lgkmcnt(0)
	v_mfma_f32_32x32x16_bf16 v[2:17], v[146:149], v[118:121], v[2:17]
	s_waitcnt vmcnt(4)
	s_barrier
	s_add_i32 s13, s13, -1
	s_cmp_lg_u32 s13, 0
	s_mov_b32 s2, s12
	s_mov_b32 s14, s63
	v_mfma_f32_32x32x16_bf16 v[2:17], v[150:153], v[122:125], v[2:17]
	v_mfma_f32_32x32x16_bf16 v[2:17], v[170:173], v[126:129], v[2:17]
	v_mfma_f32_32x32x16_bf16 v[2:17], v[98:101], v[174:177], v[2:17]
	s_cbranch_scc1 .LBB0_821
	s_branch .LBB0_823

.LBB0_969:
	s_cmp_lt_i32 s83, s7
	s_cselect_b64 s[18:19], -1, 0
	s_and_b64 s[34:35], s[18:19], exec
	s_cselect_b32 s2, 0x98000, 0
	s_cmp_lg_u64 s[18:19], 0
	v_add_u32_e32 v186, s2, v186
	v_add_u32_e32 v187, s2, v187
	s_addc_u32 s83, s83, 0
	v_lshl_add_u32 v181, s57, 14, v15
	v_lshl_add_u32 v213, s13, 8, v212
	v_add_u32_e32 v10, v181, v188
	ds_read_b128 v[2:5], v213
	ds_read_b128 v[6:9], v10
	ds_read_b128 v[10:13], v10 offset:8192
	s_waitcnt lgkmcnt(0)
	v_mfma_f32_32x32x16_bf16 v[128:143], v[10:13], v[144:147], 0
	v_sub_f32_e32 v2, v180, v2
	v_sub_f32_e32 v3, v180, v3
	v_sub_f32_e32 v4, v180, v4
	v_sub_f32_e32 v5, v180, v5
	v_fmac_f32_e32 v2, 0x3e0293ee, v96
	v_fmac_f32_e32 v3, 0x3e0293ee, v97
	v_fmac_f32_e32 v4, 0x3e0293ee, v98
	v_fmac_f32_e32 v5, 0x3e0293ee, v99
	v_exp_f32_e32 v214, v2
	v_exp_f32_e32 v215, v3
	v_exp_f32_e32 v222, v4
	v_exp_f32_e32 v223, v5
	v_mfma_f32_32x32x16_bf16 v[112:127], v[6:9], v[144:147], 0
	ds_read_b128 v[2:5], v213 offset:32
	v_add_u32_e32 v10, v181, v189
	ds_read_b128 v[6:9], v10
	ds_read_b128 v[10:13], v10 offset:8192
	s_waitcnt lgkmcnt(0)
	v_mfma_f32_32x32x16_bf16 v[112:127], v[6:9], v[148:151], v[112:127]
	v_sub_f32_e32 v2, v180, v2
	v_sub_f32_e32 v3, v180, v3
	v_sub_f32_e32 v4, v180, v4
	v_sub_f32_e32 v5, v180, v5
	v_fmac_f32_e32 v2, 0x3e0293ee, v100
	v_fmac_f32_e32 v3, 0x3e0293ee, v101
	v_fmac_f32_e32 v4, 0x3e0293ee, v102
	v_fmac_f32_e32 v5, 0x3e0293ee, v103
	v_exp_f32_e32 v100, v2
	v_exp_f32_e32 v101, v3
	v_exp_f32_e32 v102, v4
	v_exp_f32_e32 v103, v5
	v_cvt_pk_bf16_f32 v2, v214, v215
	v_cvt_pk_bf16_f32 v3, v222, v223
	v_cvt_pk_bf16_f32 v4, v100, v101
	v_cvt_pk_bf16_f32 v5, v102, v103
	s_nop 0
	v_permlane32_swap_b32_e32 v2, v4
	v_permlane32_swap_b32_e32 v3, v5
	v_mfma_f32_32x32x16_bf16 v[128:143], v[10:13], v[148:151], v[128:143]
	ds_read_b128 v[6:9], v213 offset:64
	v_add_u32_e32 v96, v181, v190
	ds_read_b128 v[10:13], v96
	ds_read_b128 v[96:99], v96 offset:8192
	s_waitcnt lgkmcnt(0)
	v_mfma_f32_32x32x16_bf16 v[128:143], v[96:99], v[152:155], v[128:143]
	v_sub_f32_e32 v6, v180, v6
	v_sub_f32_e32 v7, v180, v7
	v_fmac_f32_e32 v6, 0x3e0293ee, v104
	v_fmac_f32_e32 v7, 0x3e0293ee, v105
	v_sub_f32_e32 v8, v180, v8
	v_sub_f32_e32 v9, v180, v9
	v_fmac_f32_e32 v8, 0x3e0293ee, v106
	v_fmac_f32_e32 v9, 0x3e0293ee, v107
	v_exp_f32_e32 v104, v6
	v_exp_f32_e32 v105, v7
	v_pk_add_f32 v[6:7], v[182:183], v[214:215]
	v_exp_f32_e32 v182, v8
	v_pk_add_f32 v[6:7], v[222:223], v[6:7]
	v_exp_f32_e32 v183, v9
	v_pk_add_f32 v[6:7], v[6:7], v[100:101]
	v_mfma_f32_32x32x16_bf16 v[112:127], v[10:13], v[152:155], v[112:127]
	v_add_f32_e64 v6, v102, v6
	v_add_f32_e64 v7, v103, v7
	v_add_f32_e64 v106, v6, v104
	v_add_f32_e64 v107, v7, v105
	ds_read_b128 v[6:9], v213 offset:96
	v_add_u32_e32 v96, v181, v191
	ds_read_b128 v[10:13], v96
	ds_read_b128 v[96:99], v96 offset:8192
	s_waitcnt lgkmcnt(0)
	v_mfma_f32_32x32x16_bf16 v[112:127], v[10:13], v[156:159], v[112:127]
	v_sub_f32_e32 v6, v180, v6
	v_sub_f32_e32 v7, v180, v7
	v_sub_f32_e32 v8, v180, v8
	v_sub_f32_e32 v9, v180, v9
	v_fmac_f32_e32 v6, 0x3e0293ee, v108
	v_fmac_f32_e32 v7, 0x3e0293ee, v109
	v_fmac_f32_e32 v8, 0x3e0293ee, v110
	v_fmac_f32_e32 v9, 0x3e0293ee, v111
	v_exp_f32_e32 v108, v6
	v_exp_f32_e32 v109, v7
	v_exp_f32_e32 v110, v8
	v_exp_f32_e32 v111, v9
	v_cvt_pk_bf16_f32 v6, v104, v105
	v_cvt_pk_bf16_f32 v7, v182, v183
	v_cvt_pk_bf16_f32 v8, v108, v109
	v_cvt_pk_bf16_f32 v9, v110, v111
	s_nop 0
	v_permlane32_swap_b32_e32 v6, v8
	v_permlane32_swap_b32_e32 v7, v9
	v_mfma_f32_32x32x16_bf16 v[128:143], v[96:99], v[156:159], v[128:143]
	v_add_u32_e32 v100, v181, v192
	ds_read_b128 v[10:13], v213 offset:128
	ds_read_b128 v[96:99], v100
	ds_read_b128 v[100:103], v100 offset:8192
	s_waitcnt lgkmcnt(0)
	v_mfma_f32_32x32x16_bf16 v[128:143], v[100:103], v[160:163], v[128:143]
	v_sub_f32_e32 v10, v180, v10
	v_sub_f32_e32 v11, v180, v11
	v_fmac_f32_e32 v10, 0x3e0293ee, v80
	v_fmac_f32_e32 v11, 0x3e0293ee, v81
	v_exp_f32_e32 v104, v10
	v_exp_f32_e32 v105, v11
	v_sub_f32_e32 v12, v180, v12
	v_sub_f32_e32 v13, v180, v13
	v_fmac_f32_e32 v12, 0x3e0293ee, v82
	v_fmac_f32_e32 v13, 0x3e0293ee, v83
	v_exp_f32_e32 v214, v12
	v_exp_f32_e32 v215, v13
	v_mfma_f32_32x32x16_bf16 v[112:127], v[96:99], v[160:163], v[112:127]
	ds_read_b128 v[10:13], v213 offset:160
	v_add_u32_e32 v96, v181, v193
	ds_read_b128 v[80:83], v96
	ds_read_b128 v[96:99], v96 offset:8192
	s_waitcnt lgkmcnt(0)
	v_mfma_f32_32x32x16_bf16 v[112:127], v[80:83], v[164:167], v[112:127]
	v_sub_f32_e32 v10, v180, v10
	v_sub_f32_e32 v11, v180, v11
	v_sub_f32_e32 v12, v180, v12
	v_sub_f32_e32 v13, v180, v13
	v_fmac_f32_e32 v10, 0x3e0293ee, v84
	v_fmac_f32_e32 v11, 0x3e0293ee, v85
	v_fmac_f32_e32 v12, 0x3e0293ee, v86
	v_fmac_f32_e32 v13, 0x3e0293ee, v87
	v_exp_f32_e32 v100, v10
	v_exp_f32_e32 v101, v11
	v_exp_f32_e32 v102, v12
	v_exp_f32_e32 v103, v13
	v_cvt_pk_bf16_f32 v10, v104, v105
	v_cvt_pk_bf16_f32 v11, v214, v215
	v_cvt_pk_bf16_f32 v12, v100, v101
	v_cvt_pk_bf16_f32 v13, v102, v103
	s_nop 0
	v_permlane32_swap_b32_e32 v10, v12
	v_permlane32_swap_b32_e32 v11, v13
	v_mfma_f32_32x32x16_bf16 v[128:143], v[96:99], v[164:167], v[128:143]
	v_add_u32_e32 v96, v181, v194
	ds_read_b128 v[80:83], v213 offset:192
	ds_read_b128 v[84:87], v96
	ds_read_b128 v[96:99], v96 offset:8192
	s_waitcnt lgkmcnt(0)
; #define SBAR() __builtin_amdgcn_sched_barrier(0)
; #define VSET(S, d0) do { constexpr int b_ = (d0) * 512; TRRD(S##l0, b_); TRRD(S##h0, b_ + 2048); TRRD(S##l1, b_ + 4096); TRRD(S##h1, b_ + 6144); \
;         TRRD(S##l2, b_ + 8192); TRRD(S##h2, b_ + 10240); TRRD(S##l3, b_ + 12288); TRRD(S##h3, b_ + 14336); } while (0)
; #define LWAIT(n) do { asm volatile("s_waitcnt lgkmcnt(" #n ")" ::: "memory"); SBAR(); } while (0)
; __device__ __forceinline__ void pv_tile(f32x16* o, unsigned vb, bf16x8 pa0, bf16x8 pa1, bf16x8 pa2, bf16x8 pa3) {
;     ...
;     s16x4 Al0, Al1, Al2, Al3, Ah0, Ah1, Ah2, Ah3, Bl0, Bl1, Bl2, Bl3, Bh0, Bh1, Bh2, Bh3;
;     VSET(A, 0);
;     VSET(B, 1); LWAIT(8); VMMA(A, 0); SBAR();
;     VSET(A, 2); LWAIT(8); VMMA(B, 1); SBAR();
;     VSET(B, 3); LWAIT(8); VMMA(A, 2); SBAR();
;     LWAIT(0); VMMA(B, 3);
	v_mfma_f32_32x32x16_bf16 v[128:143], v[96:99], v[168:171], v[128:143]
	v_sub_f32_e32 v80, v180, v80
	v_sub_f32_e32 v81, v180, v81
	v_sub_f32_e32 v82, v180, v82
	v_sub_f32_e32 v83, v180, v83
	v_fmac_f32_e32 v80, 0x3e0293ee, v88
	v_fmac_f32_e32 v81, 0x3e0293ee, v89
	v_fmac_f32_e32 v82, 0x3e0293ee, v90
	v_fmac_f32_e32 v83, 0x3e0293ee, v91
	v_exp_f32_e32 v88, v80
	v_exp_f32_e32 v89, v81
	v_exp_f32_e32 v90, v82
	v_exp_f32_e32 v91, v83
	v_mfma_f32_32x32x16_bf16 v[112:127], v[84:87], v[168:171], v[112:127]
	ds_read_b128 v[80:83], v213 offset:224
	v_add_u32_e32 v96, v181, v195
	ds_read_b128 v[84:87], v96
	ds_read_b128 v[232:235], v96 offset:8192
	v_cvt_pk_bf16_f32 v236, v88, v89
	v_cvt_pk_bf16_f32 v237, v90, v91
	s_waitcnt lgkmcnt(0)
	v_sub_f32_e32 v80, v180, v80
	v_sub_f32_e32 v81, v180, v81
	v_fmac_f32_e32 v80, 0x3e0293ee, v92
	v_fmac_f32_e32 v81, 0x3e0293ee, v93
	v_pk_add_f32 v[92:93], v[182:183], v[106:107]
	v_sub_f32_e32 v82, v180, v82
	v_pk_add_f32 v[92:93], v[92:93], v[108:109]
	v_sub_f32_e32 v83, v180, v83
	v_pk_add_f32 v[92:93], v[110:111], v[92:93]
	v_fmac_f32_e32 v82, 0x3e0293ee, v94
	v_pk_add_f32 v[92:93], v[92:93], v[104:105]
	v_fmac_f32_e32 v83, 0x3e0293ee, v95
	v_pk_add_f32 v[92:93], v[214:215], v[92:93]
	v_exp_f32_e32 v80, v80
	v_exp_f32_e32 v81, v81
	v_pk_add_f32 v[92:93], v[92:93], v[100:101]
	v_exp_f32_e32 v82, v82
	v_exp_f32_e32 v83, v83
	v_pk_add_f32 v[92:93], v[102:103], v[92:93]
	v_pk_add_f32 v[92:93], v[92:93], v[88:89]
	v_pk_add_f32 v[92:93], v[90:91], v[92:93]
	v_pk_add_f32 v[92:93], v[92:93], v[80:81]
	v_pk_add_f32 v[182:183], v[82:83], v[92:93]
	v_cvt_pk_bf16_f32 v238, v80, v81
	v_mfma_f32_32x32x16_bf16 v[96:111], v[84:87], v[172:175], v[112:127]
	v_cvt_pk_bf16_f32 v239, v82, v83
	v_permlane32_swap_b32_e32 v236, v238
	v_mfma_f32_32x32x16_bf16 v[80:95], v[232:235], v[172:175], v[128:143]
	v_permlane32_swap_b32_e32 v237, v239
	v_add_u32_e32 v181, s15, v179
	ds_read_b64_tr_b16 v[112:113], v181 offset:0
	ds_read_b64_tr_b16 v[114:115], v181 offset:0x800
	ds_read_b64_tr_b16 v[116:117], v181 offset:0x1000
	ds_read_b64_tr_b16 v[118:119], v181 offset:0x1800
	ds_read_b64_tr_b16 v[120:121], v181 offset:0x2000
	ds_read_b64_tr_b16 v[122:123], v181 offset:0x2800
	ds_read_b64_tr_b16 v[124:125], v181 offset:0x3000
	ds_read_b64_tr_b16 v[126:127], v181 offset:0x3800
	ds_read_b64_tr_b16 v[128:129], v181 offset:0x200
	ds_read_b64_tr_b16 v[130:131], v181 offset:0xa00
	ds_read_b64_tr_b16 v[132:133], v181 offset:0x1200
	ds_read_b64_tr_b16 v[134:135], v181 offset:0x1a00
	ds_read_b64_tr_b16 v[136:137], v181 offset:0x2200
	ds_read_b64_tr_b16 v[138:139], v181 offset:0x2a00
	ds_read_b64_tr_b16 v[140:141], v181 offset:0x3200
	ds_read_b64_tr_b16 v[142:143], v181 offset:0x3a00
	s_waitcnt lgkmcnt(8)
	s_nop 0
	v_mfma_f32_32x32x16_bf16 v[64:79], v[2:5], v[112:115], v[64:79]
	v_mfma_f32_32x32x16_bf16 v[64:79], v[6:9], v[116:119], v[64:79]
	v_mfma_f32_32x32x16_bf16 v[64:79], v[10:13], v[120:123], v[64:79]
	v_mfma_f32_32x32x16_bf16 v[64:79], v[236:239], v[124:127], v[64:79]
	ds_read_b64_tr_b16 v[112:113], v181 offset:0x400
	ds_read_b64_tr_b16 v[114:115], v181 offset:0xc00
	ds_read_b64_tr_b16 v[116:117], v181 offset:0x1400
	ds_read_b64_tr_b16 v[118:119], v181 offset:0x1c00
	ds_read_b64_tr_b16 v[120:121], v181 offset:0x2400
	ds_read_b64_tr_b16 v[122:123], v181 offset:0x2c00
	ds_read_b64_tr_b16 v[124:125], v181 offset:0x3400
	ds_read_b64_tr_b16 v[126:127], v181 offset:0x3c00
	s_waitcnt lgkmcnt(8)
	v_mfma_f32_32x32x16_bf16 v[48:63], v[2:5], v[128:131], v[48:63]
	v_mfma_f32_32x32x16_bf16 v[48:63], v[6:9], v[132:135], v[48:63]
	v_mfma_f32_32x32x16_bf16 v[48:63], v[10:13], v[136:139], v[48:63]
	v_mfma_f32_32x32x16_bf16 v[48:63], v[236:239], v[140:143], v[48:63]
	ds_read_b64_tr_b16 v[128:129], v181 offset:0x600
	ds_read_b64_tr_b16 v[130:131], v181 offset:0xe00
	ds_read_b64_tr_b16 v[132:133], v181 offset:0x1600
	ds_read_b64_tr_b16 v[134:135], v181 offset:0x1e00
	ds_read_b64_tr_b16 v[136:137], v181 offset:0x2600
	ds_read_b64_tr_b16 v[138:139], v181 offset:0x2e00
	ds_read_b64_tr_b16 v[140:141], v181 offset:0x3600
	ds_read_b64_tr_b16 v[142:143], v181 offset:0x3e00
	s_waitcnt lgkmcnt(8)
	v_mfma_f32_32x32x16_bf16 v[32:47], v[2:5], v[112:115], v[32:47]
	v_mfma_f32_32x32x16_bf16 v[32:47], v[6:9], v[116:119], v[32:47]
	v_mfma_f32_32x32x16_bf16 v[32:47], v[10:13], v[120:123], v[32:47]
	v_mfma_f32_32x32x16_bf16 v[32:47], v[236:239], v[124:127], v[32:47]
	s_waitcnt lgkmcnt(0)
	v_mfma_f32_32x32x16_bf16 v[16:31], v[2:5], v[128:131], v[16:31]
	s_waitcnt vmcnt(5)
	s_barrier
	s_add_i32 s6, s6, 1
	s_cmp_ge_i32 s6, s8
	s_mov_b32 s15, s57
	s_mov_b32 s57, s63
	v_mfma_f32_32x32x16_bf16 v[16:31], v[6:9], v[132:135], v[16:31]
	s_mov_b32 s63, s13
	v_mfma_f32_32x32x16_bf16 v[16:31], v[10:13], v[136:139], v[16:31]
	v_mfma_f32_32x32x16_bf16 v[16:31], v[236:239], v[140:143], v[16:31]
	s_cbranch_scc1 .LBB0_973
